# deferred-barrier epilogue overlap kept on 9 GEMM phases, removed from PLE_0/PLE_1
# baseline (speedup 1.0000x reference)
; #define G_STAGE(bufoff, gbase, o0, h64) do { \
;         __builtin_amdgcn_global_load_lds((const unsigned*)((const char*)(gbase) + (o0)), (LAS unsigned*)(lds + (bufoff) + ldsw), 16, 0, 0); \
;         __builtin_amdgcn_global_load_lds((const unsigned*)((const char*)(gbase) + (h64) + (o0)), (LAS unsigned*)(lds + (bufoff) + ldsw + 8192), 16, 0, 0); } while (0)
; #define G_LDA(dst, b, h) do { _Pragma("unroll") for (int m = 0; m < 4; ++m) _Pragma("unroll") for (int k = 0; k < 2; ++k) dst[m][k] = *(const LAS bf16x8*)(lds + G_SA(b, h) + aoff + m * 2048 + k * 1024); } while (0)
; #define G_LDB(dst, b, h) do { _Pragma("unroll") for (int n = 0; n < 2; ++n) _Pragma("unroll") for (int k = 0; k < 2; ++k) dst[n][k] = *(const LAS bf16x8*)(lds + G_SB(b, h) + boff + n * 2048 + k * 1024); } while (0)
; #define G_WAIT_L(n) asm volatile("s_waitcnt lgkmcnt(" #n ")" ::: "memory")
; #define G_BAR __builtin_amdgcn_s_barrier()
; #define G_SCHED __builtin_amdgcn_sched_barrier(0)
;     ...
;         for (int t = 0; t < nt; t += 2) {
;             const bool last = (t == nt - 2);
;             const char* a1 = cA + (size_t)(t + 1) * ckA;
;             const char* a2 = last ? nA : cA + (size_t)(t + 2) * ckA; const char* b2 = last ? nB : cB + (size_t)(t + 2) * kB;
;             const char* a3 = a2 + ckA; const char* b3 = b2 + kB;
;             G_LDB(B0, 0, 0); G_SCHED; G_LDA(At, 0, 0); G_STAGE(G_SA(1, 1), a1 + chA, cA0, qA);
;             G_WAIT_L(8); G_BAR; G_WAIT_L(0); G_MMA(0, 0, At, B0); G_BAR; G_SCHED;
;             G_LDB(B1, 0, 1); G_STAGE(G_SB(0, 0), b2, cB0, qB);
;             G_BAR; G_WAIT_L(0); G_MMA(0, 1, At, B1); G_BAR;
;             G_LDA(At, 0, 1); G_STAGE(G_SA(0, 0), a2, cA0, qA);
;             G_BAR; G_WAIT_L(0); G_MMA(1, 0, At, B0); G_BAR; G_SCHED;
.LBB0_1260:
	s_add_u32 s22, s10, s18
	s_addc_u32 s23, s11, s19
	s_add_u32 s20, s22, 0x100
	s_addc_u32 s21, s23, 0
	s_and_b64 s[4:5], s[16:17], exec
	s_cselect_b32 s20, s6, s20
	s_cselect_b32 s21, s7, s21
	s_add_u32 s4, s12, s18
	s_addc_u32 s5, s13, s19
	s_add_u32 s18, s4, 0x100
	s_addc_u32 s19, s5, 0
	s_add_i32 s44, 0, 0x10000
	v_add_u32_e32 v139, s44, v137
	ds_read_b128 v[140:143], v139
	ds_read_b128 v[144:147], v139 offset:1024
	ds_read_b128 v[148:151], v139 offset:2048
	ds_read_b128 v[152:155], v139 offset:3072
	s_and_b64 s[4:5], s[16:17], exec
	s_cselect_b32 s16, s8, s18
	s_cselect_b32 s17, s9, s19
	s_add_i32 s5, 0, 0x14000
	s_add_i32 s43, 0, 0x18000
	s_add_i32 s18, 0, 0x1c000
	s_add_i32 s45, s44, s25
	s_add_i32 s51, s5, s25
	s_add_i32 s19, s43, s25
	s_add_i32 s53, s18, s25
	s_mov_b64 s[64:65], 0x8000
	s_mov_b64 s[62:63], 0x10080
	s_add_i32 m0, s31, 0xc000
	s_add_i32 s4, s31, 0xe000
	s_add_i32 s54, s45, 0x2000
	s_add_i32 s50, s51, 0x2000
	s_add_i32 s44, s19, 0x2000
	s_add_i32 s52, s53, 0x2000
	v_lshl_add_u64 v[184:185], s[22:23], 0, v[2:3]
	v_lshl_add_u64 v[204:205], v[184:185], 0, s[62:63]
	ds_read_b128 v[156:159], v138
	ds_read_b128 v[160:163], v138 offset:1024
	ds_read_b128 v[164:167], v138 offset:2048
	ds_read_b128 v[172:175], v138 offset:3072
	ds_read_b128 v[176:179], v138 offset:4096
	ds_read_b128 v[180:183], v138 offset:5120
	ds_read_b128 v[196:199], v138 offset:6144
	ds_read_b128 v[200:203], v138 offset:7168
	global_load_lds_dwordx4 v[204:205], off
	v_lshl_add_u64 v[184:185], v[184:185], 0, s[68:69]
	s_mov_b32 m0, s4
	s_nop 0
	global_load_lds_dwordx4 v[184:185], off
	s_waitcnt lgkmcnt(8)
	s_barrier
	s_waitcnt lgkmcnt(0)
	s_waitcnt lgkmcnt(0)
	v_mfma_f32_16x16x32_bf16 v[132:135], v[140:143], v[156:159], v[132:135]
	v_mfma_f32_16x16x32_bf16 v[128:131], v[148:151], v[156:159], v[128:131]
	v_mfma_f32_16x16x32_bf16 v[124:127], v[140:143], v[164:167], v[124:127]
	v_mfma_f32_16x16x32_bf16 v[116:119], v[148:151], v[164:167], v[116:119]
	v_mfma_f32_16x16x32_bf16 v[108:111], v[140:143], v[176:179], v[108:111]
	v_mfma_f32_16x16x32_bf16 v[100:103], v[148:151], v[176:179], v[100:103]
	v_mfma_f32_16x16x32_bf16 v[92:95], v[140:143], v[196:199], v[92:95]
	v_mfma_f32_16x16x32_bf16 v[84:87], v[148:151], v[196:199], v[84:87]
	v_mfma_f32_16x16x32_bf16 v[132:135], v[144:147], v[160:163], v[132:135]
	v_mfma_f32_16x16x32_bf16 v[128:131], v[152:155], v[160:163], v[128:131]
	v_mfma_f32_16x16x32_bf16 v[124:127], v[144:147], v[172:175], v[124:127]
	v_mfma_f32_16x16x32_bf16 v[116:119], v[152:155], v[172:175], v[116:119]
	v_mfma_f32_16x16x32_bf16 v[108:111], v[144:147], v[180:183], v[108:111]
	v_mfma_f32_16x16x32_bf16 v[100:103], v[152:155], v[180:183], v[100:103]
	v_mfma_f32_16x16x32_bf16 v[92:95], v[144:147], v[200:203], v[92:95]
	v_mfma_f32_16x16x32_bf16 v[84:87], v[152:155], v[200:203], v[84:87]
	s_barrier
	s_mov_b32 m0, s45
	v_add_u32_e32 v139, s5, v137
	v_lshl_add_u64 v[184:185], s[16:17], 0, v[0:1]
	ds_read_b128 v[204:207], v139
	ds_read_b128 v[208:211], v139 offset:1024
	ds_read_b128 v[212:215], v139 offset:2048
	ds_read_b128 v[216:219], v139 offset:3072
	global_load_lds_dwordx4 v[184:185], off
	v_lshl_add_u64 v[220:221], v[184:185], 0, s[64:65]
	s_mov_b32 m0, s54
	s_nop 0
	global_load_lds_dwordx4 v[220:221], off
	s_barrier
	s_waitcnt lgkmcnt(0)
	s_waitcnt lgkmcnt(0)
	v_mfma_f32_16x16x32_bf16 v[120:123], v[204:207], v[156:159], v[120:123]
	v_mfma_f32_16x16x32_bf16 v[112:115], v[212:215], v[156:159], v[112:115]
	v_mfma_f32_16x16x32_bf16 v[104:107], v[204:207], v[164:167], v[104:107]
	v_mfma_f32_16x16x32_bf16 v[96:99], v[212:215], v[164:167], v[96:99]
	v_mfma_f32_16x16x32_bf16 v[88:91], v[204:207], v[176:179], v[88:91]
	v_mfma_f32_16x16x32_bf16 v[80:83], v[212:215], v[176:179], v[80:83]
	v_mfma_f32_16x16x32_bf16 v[76:79], v[204:207], v[196:199], v[76:79]
	v_mfma_f32_16x16x32_bf16 v[72:75], v[212:215], v[196:199], v[72:75]
	v_mfma_f32_16x16x32_bf16 v[120:123], v[208:211], v[160:163], v[120:123]
	v_mfma_f32_16x16x32_bf16 v[112:115], v[216:219], v[160:163], v[112:115]
	v_mfma_f32_16x16x32_bf16 v[104:107], v[208:211], v[172:175], v[104:107]
	v_mfma_f32_16x16x32_bf16 v[96:99], v[216:219], v[172:175], v[96:99]
	v_mfma_f32_16x16x32_bf16 v[88:91], v[208:211], v[180:183], v[88:91]
	v_mfma_f32_16x16x32_bf16 v[80:83], v[216:219], v[180:183], v[80:83]
	v_mfma_f32_16x16x32_bf16 v[76:79], v[208:211], v[200:203], v[76:79]
	v_mfma_f32_16x16x32_bf16 v[72:75], v[216:219], v[200:203], v[72:75]
	s_mov_b32 m0, s31
	v_lshl_add_u64 v[220:221], s[20:21], 0, v[2:3]
	s_mov_b64 s[4:5], 0x8000
	s_barrier
	ds_read_b128 v[156:159], v138 offset:16384
	ds_read_b128 v[160:163], v138 offset:17408
	ds_read_b128 v[164:167], v138 offset:18432
	ds_read_b128 v[172:175], v138 offset:19456
	ds_read_b128 v[176:179], v138 offset:20480
	ds_read_b128 v[180:183], v138 offset:21504
	ds_read_b128 v[196:199], v138 offset:22528
	ds_read_b128 v[200:203], v138 offset:23552
	global_load_lds_dwordx4 v[220:221], off
	v_lshl_add_u64 v[222:223], v[220:221], 0, s[4:5]
	s_mov_b32 m0, s33
	s_mov_b64 s[16:17], 0x18000
	global_load_lds_dwordx4 v[222:223], off
	s_barrier
; #define G_STAGE(bufoff, gbase, o0, h64) do { \
;         __builtin_amdgcn_global_load_lds((const unsigned*)((const char*)(gbase) + (o0)), (LAS unsigned*)(lds + (bufoff) + ldsw), 16, 0, 0); \
;         __builtin_amdgcn_global_load_lds((const unsigned*)((const char*)(gbase) + (h64) + (o0)), (LAS unsigned*)(lds + (bufoff) + ldsw + 8192), 16, 0, 0); } while (0)
; #define G_LDA(dst, b, h) do { _Pragma("unroll") for (int m = 0; m < 4; ++m) _Pragma("unroll") for (int k = 0; k < 2; ++k) dst[m][k] = *(const LAS bf16x8*)(lds + G_SA(b, h) + aoff + m * 2048 + k * 1024); } while (0)
; #define G_LDB(dst, b, h) do { _Pragma("unroll") for (int n = 0; n < 2; ++n) _Pragma("unroll") for (int k = 0; k < 2; ++k) dst[n][k] = *(const LAS bf16x8*)(lds + G_SB(b, h) + boff + n * 2048 + k * 1024); } while (0)
; #define G_WAIT_V(n) asm volatile("s_waitcnt vmcnt(" #n ")" ::: "memory")
; #define G_WAIT_L(n) asm volatile("s_waitcnt lgkmcnt(" #n ")" ::: "memory")
; #define G_BAR __builtin_amdgcn_s_barrier()
; #define G_SCHED __builtin_amdgcn_sched_barrier(0)
;     ...
;             G_BAR; G_WAIT_L(0); G_MMA(1, 0, At, B0); G_BAR; G_SCHED;
;             G_STAGE(G_SB(0, 1), b2 + chB, cB0, qB);
;             G_WAIT_V(6); G_BAR; G_MMA(1, 1, At, B1); G_BAR;
;             G_LDB(B0, 1, 0); G_SCHED; G_LDA(At, 1, 0); G_STAGE(G_SA(0, 1), a2 + chA, cA0, qA);
;             G_WAIT_L(8); G_BAR; G_WAIT_L(0); G_MMA(0, 0, At, B0); G_BAR; G_SCHED;
;             G_LDB(B1, 1, 1); G_STAGE(G_SB(1, 0), b3, cB0, qB);
;             G_BAR; G_WAIT_L(0); G_MMA(0, 1, At, B1); G_BAR;
	s_waitcnt lgkmcnt(0)
	s_mov_b64 s[20:21], 0x8080
	s_waitcnt lgkmcnt(0)
	v_mfma_f32_16x16x32_bf16 v[68:71], v[140:143], v[156:159], v[68:71]
	v_mfma_f32_16x16x32_bf16 v[64:67], v[148:151], v[156:159], v[64:67]
	v_mfma_f32_16x16x32_bf16 v[60:63], v[140:143], v[164:167], v[60:63]
	v_mfma_f32_16x16x32_bf16 v[52:55], v[148:151], v[164:167], v[52:55]
	v_mfma_f32_16x16x32_bf16 v[44:47], v[140:143], v[176:179], v[44:47]
	v_mfma_f32_16x16x32_bf16 v[36:39], v[148:151], v[176:179], v[36:39]
	v_mfma_f32_16x16x32_bf16 v[28:31], v[140:143], v[196:199], v[28:31]
	v_mfma_f32_16x16x32_bf16 v[20:23], v[148:151], v[196:199], v[20:23]
	v_mfma_f32_16x16x32_bf16 v[68:71], v[144:147], v[160:163], v[68:71]
	v_mfma_f32_16x16x32_bf16 v[64:67], v[152:155], v[160:163], v[64:67]
	v_mfma_f32_16x16x32_bf16 v[60:63], v[144:147], v[172:175], v[60:63]
	v_mfma_f32_16x16x32_bf16 v[52:55], v[152:155], v[172:175], v[52:55]
	v_mfma_f32_16x16x32_bf16 v[44:47], v[144:147], v[180:183], v[44:47]
	v_mfma_f32_16x16x32_bf16 v[36:39], v[152:155], v[180:183], v[36:39]
	v_mfma_f32_16x16x32_bf16 v[28:31], v[144:147], v[200:203], v[28:31]
	v_mfma_f32_16x16x32_bf16 v[20:23], v[152:155], v[200:203], v[20:23]
	s_barrier
	s_mov_b32 m0, s51
	v_lshl_add_u64 v[140:141], v[184:185], 0, s[58:59]
	global_load_lds_dwordx4 v[140:141], off
	v_lshl_add_u64 v[140:141], v[184:185], 0, s[16:17]
	s_mov_b32 m0, s50
	s_nop 0
	global_load_lds_dwordx4 v[140:141], off
	s_waitcnt vmcnt(6)
	s_barrier
	v_mfma_f32_16x16x32_bf16 v[56:59], v[204:207], v[156:159], v[56:59]
	v_mfma_f32_16x16x32_bf16 v[48:51], v[212:215], v[156:159], v[48:51]
	v_mfma_f32_16x16x32_bf16 v[40:43], v[204:207], v[164:167], v[40:43]
	v_mfma_f32_16x16x32_bf16 v[32:35], v[212:215], v[164:167], v[32:35]
	v_mfma_f32_16x16x32_bf16 v[24:27], v[204:207], v[176:179], v[24:27]
	v_mfma_f32_16x16x32_bf16 v[16:19], v[212:215], v[176:179], v[16:19]
	v_mfma_f32_16x16x32_bf16 v[12:15], v[204:207], v[196:199], v[12:15]
	v_mfma_f32_16x16x32_bf16 v[8:11], v[212:215], v[196:199], v[8:11]
	v_mfma_f32_16x16x32_bf16 v[56:59], v[208:211], v[160:163], v[56:59]
	v_mfma_f32_16x16x32_bf16 v[48:51], v[216:219], v[160:163], v[48:51]
	v_mfma_f32_16x16x32_bf16 v[40:43], v[208:211], v[172:175], v[40:43]
	v_mfma_f32_16x16x32_bf16 v[32:35], v[216:219], v[172:175], v[32:35]
	v_mfma_f32_16x16x32_bf16 v[24:27], v[208:211], v[180:183], v[24:27]
	v_mfma_f32_16x16x32_bf16 v[16:19], v[216:219], v[180:183], v[16:19]
	v_mfma_f32_16x16x32_bf16 v[12:15], v[208:211], v[200:203], v[12:15]
	v_mfma_f32_16x16x32_bf16 v[8:11], v[216:219], v[200:203], v[8:11]
	v_add_u32_e32 v139, s43, v137
	s_barrier
	ds_read_b128 v[140:143], v139
	ds_read_b128 v[144:147], v139 offset:1024
	ds_read_b128 v[148:151], v139 offset:2048
	ds_read_b128 v[152:155], v139 offset:3072
	s_mov_b32 m0, s34
	v_lshl_add_u64 v[204:205], v[220:221], 0, s[58:59]
	ds_read_b128 v[156:159], v138 offset:32768
	ds_read_b128 v[160:163], v138 offset:33792
	ds_read_b128 v[164:167], v138 offset:34816
	ds_read_b128 v[172:175], v138 offset:35840
	ds_read_b128 v[176:179], v138 offset:36864
	ds_read_b128 v[180:183], v138 offset:37888
	ds_read_b128 v[196:199], v138 offset:38912
	ds_read_b128 v[200:203], v138 offset:39936
	global_load_lds_dwordx4 v[204:205], off
	v_lshl_add_u64 v[204:205], v[220:221], 0, s[16:17]
	s_mov_b32 m0, s35
	s_nop 0
	global_load_lds_dwordx4 v[204:205], off
	s_waitcnt lgkmcnt(8)
	s_barrier
	s_waitcnt lgkmcnt(0)
	s_waitcnt lgkmcnt(0)
	v_mfma_f32_16x16x32_bf16 v[132:135], v[140:143], v[156:159], v[132:135]
	v_mfma_f32_16x16x32_bf16 v[128:131], v[148:151], v[156:159], v[128:131]
	v_mfma_f32_16x16x32_bf16 v[124:127], v[140:143], v[164:167], v[124:127]
	v_mfma_f32_16x16x32_bf16 v[116:119], v[148:151], v[164:167], v[116:119]
	v_mfma_f32_16x16x32_bf16 v[108:111], v[140:143], v[176:179], v[108:111]
	v_mfma_f32_16x16x32_bf16 v[100:103], v[148:151], v[176:179], v[100:103]
	v_mfma_f32_16x16x32_bf16 v[92:95], v[140:143], v[196:199], v[92:95]
	v_mfma_f32_16x16x32_bf16 v[84:87], v[148:151], v[196:199], v[84:87]
	v_mfma_f32_16x16x32_bf16 v[132:135], v[144:147], v[160:163], v[132:135]
	v_mfma_f32_16x16x32_bf16 v[128:131], v[152:155], v[160:163], v[128:131]
	v_mfma_f32_16x16x32_bf16 v[124:127], v[144:147], v[172:175], v[124:127]
	v_mfma_f32_16x16x32_bf16 v[116:119], v[152:155], v[172:175], v[116:119]
	v_mfma_f32_16x16x32_bf16 v[108:111], v[144:147], v[180:183], v[108:111]
	v_mfma_f32_16x16x32_bf16 v[100:103], v[152:155], v[180:183], v[100:103]
	v_mfma_f32_16x16x32_bf16 v[92:95], v[144:147], v[200:203], v[92:95]
	v_mfma_f32_16x16x32_bf16 v[84:87], v[152:155], v[200:203], v[84:87]
	s_barrier
	s_mov_b32 m0, s19
	v_add_u32_e32 v139, s18, v137
	v_lshl_add_u64 v[222:223], v[184:185], 0, s[46:47]
	ds_read_b128 v[204:207], v139
	ds_read_b128 v[208:211], v139 offset:1024
	ds_read_b128 v[212:215], v139 offset:2048
	ds_read_b128 v[216:219], v139 offset:3072
	global_load_lds_dwordx4 v[222:223], off
	v_lshl_add_u64 v[222:223], v[184:185], 0, s[20:21]
	s_mov_b32 m0, s44
	s_mov_b64 s[4:5], 0x10080
	global_load_lds_dwordx4 v[222:223], off
	s_barrier
; #define G_STAGE(bufoff, gbase, o0, h64) do { \
;         __builtin_amdgcn_global_load_lds((const unsigned*)((const char*)(gbase) + (o0)), (LAS unsigned*)(lds + (bufoff) + ldsw), 16, 0, 0); \
;         __builtin_amdgcn_global_load_lds((const unsigned*)((const char*)(gbase) + (h64) + (o0)), (LAS unsigned*)(lds + (bufoff) + ldsw + 8192), 16, 0, 0); } while (0)
; #define G_LDA(dst, b, h) do { _Pragma("unroll") for (int m = 0; m < 4; ++m) _Pragma("unroll") for (int k = 0; k < 2; ++k) dst[m][k] = *(const LAS bf16x8*)(lds + G_SA(b, h) + aoff + m * 2048 + k * 1024); } while (0)
; #define G_WAIT_V(n) asm volatile("s_waitcnt vmcnt(" #n ")" ::: "memory")
; #define G_WAIT_L(n) asm volatile("s_waitcnt lgkmcnt(" #n ")" ::: "memory")
; #define G_BAR __builtin_amdgcn_s_barrier()
; #define G_SCHED __builtin_amdgcn_sched_barrier(0)
;     ...
;             G_BAR; G_WAIT_L(0); G_MMA(0, 1, At, B1); G_BAR;
;             G_LDA(At, 1, 1); G_STAGE(G_SA(1, 0), a3, cA0, qA);
;             G_BAR; G_WAIT_L(0); G_MMA(1, 0, At, B0); G_BAR; G_SCHED;
;             G_STAGE(G_SB(1, 1), b3 + chB, cB0, qB);
;             G_WAIT_V(6); G_BAR; G_MMA(1, 1, At, B1); G_BAR;
;         }
;         E.template run<cs.kind>(acc, cur, tid);
;         if (!has_next) break;
	s_waitcnt lgkmcnt(0)
	s_waitcnt lgkmcnt(0)
	v_mfma_f32_16x16x32_bf16 v[120:123], v[204:207], v[156:159], v[120:123]
	v_mfma_f32_16x16x32_bf16 v[112:115], v[212:215], v[156:159], v[112:115]
	v_mfma_f32_16x16x32_bf16 v[104:107], v[204:207], v[164:167], v[104:107]
	v_mfma_f32_16x16x32_bf16 v[96:99], v[212:215], v[164:167], v[96:99]
	v_mfma_f32_16x16x32_bf16 v[88:91], v[204:207], v[176:179], v[88:91]
	v_mfma_f32_16x16x32_bf16 v[80:83], v[212:215], v[176:179], v[80:83]
	v_mfma_f32_16x16x32_bf16 v[76:79], v[204:207], v[196:199], v[76:79]
	v_mfma_f32_16x16x32_bf16 v[72:75], v[212:215], v[196:199], v[72:75]
	v_mfma_f32_16x16x32_bf16 v[120:123], v[208:211], v[160:163], v[120:123]
	v_mfma_f32_16x16x32_bf16 v[112:115], v[216:219], v[160:163], v[112:115]
	v_mfma_f32_16x16x32_bf16 v[104:107], v[208:211], v[172:175], v[104:107]
	v_mfma_f32_16x16x32_bf16 v[96:99], v[216:219], v[172:175], v[96:99]
	v_mfma_f32_16x16x32_bf16 v[88:91], v[208:211], v[180:183], v[88:91]
	v_mfma_f32_16x16x32_bf16 v[80:83], v[216:219], v[180:183], v[80:83]
	v_mfma_f32_16x16x32_bf16 v[76:79], v[208:211], v[200:203], v[76:79]
	v_mfma_f32_16x16x32_bf16 v[72:75], v[216:219], v[200:203], v[72:75]
	s_mov_b32 m0, s36
	v_lshl_add_u64 v[222:223], v[220:221], 0, s[46:47]
	s_barrier
	ds_read_b128 v[156:159], v138 offset:49152
	ds_read_b128 v[160:163], v138 offset:50176
	ds_read_b128 v[164:167], v138 offset:51200
	ds_read_b128 v[172:175], v138 offset:52224
	ds_read_b128 v[176:179], v138 offset:53248
	ds_read_b128 v[180:183], v138 offset:54272
	ds_read_b128 v[196:199], v138 offset:55296
	ds_read_b128 v[200:203], v138 offset:56320
	global_load_lds_dwordx4 v[222:223], off
	v_lshl_add_u64 v[220:221], v[220:221], 0, s[20:21]
	s_mov_b32 m0, s37
	s_nop 0
	global_load_lds_dwordx4 v[220:221], off
	s_barrier
	s_waitcnt lgkmcnt(0)
	s_waitcnt lgkmcnt(0)
	v_mfma_f32_16x16x32_bf16 v[68:71], v[140:143], v[156:159], v[68:71]
	v_mfma_f32_16x16x32_bf16 v[64:67], v[148:151], v[156:159], v[64:67]
	v_mfma_f32_16x16x32_bf16 v[60:63], v[140:143], v[164:167], v[60:63]
	v_mfma_f32_16x16x32_bf16 v[52:55], v[148:151], v[164:167], v[52:55]
	v_mfma_f32_16x16x32_bf16 v[44:47], v[140:143], v[176:179], v[44:47]
	v_mfma_f32_16x16x32_bf16 v[36:39], v[148:151], v[176:179], v[36:39]
	v_mfma_f32_16x16x32_bf16 v[28:31], v[140:143], v[196:199], v[28:31]
	v_mfma_f32_16x16x32_bf16 v[20:23], v[148:151], v[196:199], v[20:23]
	v_mfma_f32_16x16x32_bf16 v[68:71], v[144:147], v[160:163], v[68:71]
	v_mfma_f32_16x16x32_bf16 v[64:67], v[152:155], v[160:163], v[64:67]
	v_mfma_f32_16x16x32_bf16 v[60:63], v[144:147], v[172:175], v[60:63]
	v_mfma_f32_16x16x32_bf16 v[52:55], v[152:155], v[172:175], v[52:55]
	v_mfma_f32_16x16x32_bf16 v[44:47], v[144:147], v[180:183], v[44:47]
	v_mfma_f32_16x16x32_bf16 v[36:39], v[152:155], v[180:183], v[36:39]
	v_mfma_f32_16x16x32_bf16 v[28:31], v[144:147], v[200:203], v[28:31]
	v_mfma_f32_16x16x32_bf16 v[20:23], v[152:155], v[200:203], v[20:23]
	s_barrier
	s_mov_b32 m0, s53
	v_lshl_add_u64 v[140:141], v[184:185], 0, s[4:5]
	global_load_lds_dwordx4 v[140:141], off
	v_lshl_add_u64 v[140:141], v[184:185], 0, s[68:69]
	s_mov_b32 m0, s52
	s_nop 0
	global_load_lds_dwordx4 v[140:141], off
	s_waitcnt vmcnt(6)
	s_barrier
	v_mfma_f32_16x16x32_bf16 v[56:59], v[204:207], v[156:159], v[56:59]
	v_mfma_f32_16x16x32_bf16 v[48:51], v[212:215], v[156:159], v[48:51]
	v_mfma_f32_16x16x32_bf16 v[40:43], v[204:207], v[164:167], v[40:43]
	v_mfma_f32_16x16x32_bf16 v[32:35], v[212:215], v[164:167], v[32:35]
	v_mfma_f32_16x16x32_bf16 v[24:27], v[204:207], v[176:179], v[24:27]
	v_mfma_f32_16x16x32_bf16 v[16:19], v[212:215], v[176:179], v[16:19]
	v_mfma_f32_16x16x32_bf16 v[12:15], v[204:207], v[196:199], v[12:15]
	v_mfma_f32_16x16x32_bf16 v[8:11], v[212:215], v[196:199], v[8:11]
	v_mfma_f32_16x16x32_bf16 v[56:59], v[208:211], v[160:163], v[56:59]
	v_mfma_f32_16x16x32_bf16 v[48:51], v[216:219], v[160:163], v[48:51]
	v_mfma_f32_16x16x32_bf16 v[40:43], v[208:211], v[172:175], v[40:43]
	v_mfma_f32_16x16x32_bf16 v[32:35], v[216:219], v[172:175], v[32:35]
	v_mfma_f32_16x16x32_bf16 v[24:27], v[208:211], v[180:183], v[24:27]
	v_mfma_f32_16x16x32_bf16 v[16:19], v[216:219], v[180:183], v[16:19]
	v_mfma_f32_16x16x32_bf16 v[12:15], v[208:211], v[200:203], v[12:15]
	v_mfma_f32_16x16x32_bf16 v[8:11], v[216:219], v[200:203], v[8:11]
	s_andn2_b64 vcc, exec, s[14:15]
	s_mov_b64 s[16:17], -1
	s_mov_b64 s[14:15], 0
	s_mov_b64 s[18:19], 0x100
	s_barrier
	s_cbranch_vccz .LBB0_1260
; __device__ __forceinline__ u32x4 pack8(const f32x4 a, const f32x4 b) { u32x4 w; w.x = cvt_pk_bf16(a[0], a[1]); w.y = cvt_pk_bf16(a[2], a[3]); w.z = cvt_pk_bf16(b[0], b[1]); w.w = cvt_pk_bf16(b[2], b[3]); return w; }
; #define MEMFENCE asm volatile("" ::: "memory")
; #define G_WAIT_V(n) asm volatile("s_waitcnt vmcnt(" #n ")" ::: "memory")
; #define G_BAR __builtin_amdgcn_s_barrier()
;     template <int KIND> __device__ __forceinline__ void run(f32x4 (&acc)[2][2][4][2], const Unit& u, int tid_in) const {
;     ...
;         if constexpr (KIND == K_PP) {
; #pragma unroll
;             for (int ai = 0; ai < 2; ++ai)
; #pragma unroll
;                 for (int m = 0; m < 4; ++m)
; #pragma unroll
;                     for (int bj = 0; bj < 2; ++bj) { scr[((ai * 4 + m) * 2 + bj) * 512 + tid] = pack8(acc[ai][bj][m][0], acc[ai][bj][m][1]); if (bj == 1) MEMFENCE; }
;         }
;     ...
;         E.template run<cs.kind>(acc, cur, tid);
;         if (!has_next) break;
;         if (!(cs.kind == K_MG_B && cur.aux < 2))
; #pragma unroll
;         for (int a = 0; a < 2; ++a)
; #pragma unroll
;             for (int b = 0; b < 2; ++b)
; #pragma unroll
;                 for (int m = 0; m < 4; ++m)
; #pragma unroll
;                     for (int n = 0; n < 2; ++n) acc[a][b][m][n] = (f32x4){0.f, 0.f, 0.f, 0.f};
;         cur = nxt; cA = nA; cB = nB; ++ui;
;     }
;     G_WAIT_V(0);
;     if (wr == 0) G_BAR;
	s_lshl_b32 s4, s42, 17
	s_and_b32 s4, s4, 0x20000
	v_mov_b32_e32 v140, v136
	s_add_u32 s4, s38, s4
	s_addc_u32 s5, s39, 0
	v_ashrrev_i32_e32 v141, 31, v140
	v_cvt_pk_bf16_f32 v132, v132, v133
	v_cvt_pk_bf16_f32 v133, v134, v135
	v_cvt_pk_bf16_f32 v134, v128, v129
	v_lshl_add_u64 v[128:129], v[140:141], 4, s[4:5]
	s_movk_i32 s4, 0x2000
	v_cvt_pk_bf16_f32 v135, v130, v131
	global_store_dwordx4 v[128:129], v[132:135], off
	v_cvt_pk_bf16_f32 v120, v120, v121
	v_cvt_pk_bf16_f32 v121, v122, v123
	v_cvt_pk_bf16_f32 v122, v112, v113
	v_add_co_u32_e32 v112, vcc, s4, v128
	v_cvt_pk_bf16_f32 v123, v114, v115
	s_movk_i32 s4, 0x6000
	s_nop 0
	v_addc_co_u32_e32 v113, vcc, 0, v129, vcc
	global_store_dwordx4 v[112:113], v[120:123], off
	v_cvt_pk_bf16_f32 v112, v124, v125
	v_cvt_pk_bf16_f32 v113, v126, v127
	v_cvt_pk_bf16_f32 v114, v116, v117
	v_add_co_u32_e32 v116, vcc, s49, v128
	v_cvt_pk_bf16_f32 v115, v118, v119
	s_mov_b32 s42, s41
	s_nop 0
	v_addc_co_u32_e32 v117, vcc, 0, v129, vcc
	global_store_dwordx4 v[116:117], v[112:115], off
	v_cvt_pk_bf16_f32 v104, v104, v105
	v_cvt_pk_bf16_f32 v105, v106, v107
	v_cvt_pk_bf16_f32 v106, v96, v97
	v_add_co_u32_e32 v96, vcc, s4, v128
	v_cvt_pk_bf16_f32 v107, v98, v99
	s_mov_b32 s4, 0xa000
	s_nop 0
	v_addc_co_u32_e32 v97, vcc, 0, v129, vcc
	global_store_dwordx4 v[96:97], v[104:107], off
	v_cvt_pk_bf16_f32 v96, v108, v109
	v_cvt_pk_bf16_f32 v97, v110, v111
	v_cvt_pk_bf16_f32 v98, v100, v101
	v_add_co_u32_e32 v100, vcc, s77, v128
	v_cvt_pk_bf16_f32 v99, v102, v103
	s_mov_b64 s[12:13], s[8:9]
	s_nop 0
	v_addc_co_u32_e32 v101, vcc, 0, v129, vcc
	global_store_dwordx4 v[100:101], v[96:99], off
	v_cvt_pk_bf16_f32 v88, v88, v89
	v_cvt_pk_bf16_f32 v89, v90, v91
	v_cvt_pk_bf16_f32 v90, v80, v81
	v_add_co_u32_e32 v80, vcc, s4, v128
	v_cvt_pk_bf16_f32 v91, v82, v83
	s_mov_b32 s4, 0xc000
	s_nop 0
	v_addc_co_u32_e32 v81, vcc, 0, v129, vcc
	global_store_dwordx4 v[80:81], v[88:91], off
	v_cvt_pk_bf16_f32 v80, v92, v93
	v_cvt_pk_bf16_f32 v81, v94, v95
	v_cvt_pk_bf16_f32 v82, v84, v85
	v_add_co_u32_e32 v84, vcc, s4, v128
	s_mov_b32 s4, 0xe000
	s_nop 0
	v_addc_co_u32_e32 v85, vcc, 0, v129, vcc
	v_cvt_pk_bf16_f32 v83, v86, v87
	global_store_dwordx4 v[84:85], v[80:83], off
	v_cvt_pk_bf16_f32 v76, v76, v77
	v_cvt_pk_bf16_f32 v77, v78, v79
	v_cvt_pk_bf16_f32 v78, v72, v73
	v_add_co_u32_e32 v72, vcc, s4, v128
	v_cvt_pk_bf16_f32 v79, v74, v75
	s_mov_b32 s4, 0x12000
	s_nop 0
	v_addc_co_u32_e32 v73, vcc, 0, v129, vcc
	global_store_dwordx4 v[72:73], v[76:79], off
	v_cvt_pk_bf16_f32 v68, v68, v69
	v_cvt_pk_bf16_f32 v69, v70, v71
	v_cvt_pk_bf16_f32 v70, v64, v65
	v_add_co_u32_e32 v64, vcc, s91, v128
	v_cvt_pk_bf16_f32 v71, v66, v67
	s_mov_b64 s[10:11], s[6:7]
	s_nop 0
	v_addc_co_u32_e32 v65, vcc, 0, v129, vcc
	global_store_dwordx4 v[64:65], v[68:71], off
	v_cvt_pk_bf16_f32 v56, v56, v57
	v_cvt_pk_bf16_f32 v57, v58, v59
	v_cvt_pk_bf16_f32 v58, v48, v49
	v_add_co_u32_e32 v48, vcc, s4, v128
	v_cvt_pk_bf16_f32 v59, v50, v51
	s_mov_b32 s4, 0x14000
	s_nop 0
	v_addc_co_u32_e32 v49, vcc, 0, v129, vcc
	global_store_dwordx4 v[48:49], v[56:59], off
	v_cvt_pk_bf16_f32 v48, v60, v61
	v_cvt_pk_bf16_f32 v49, v62, v63
	v_cvt_pk_bf16_f32 v50, v52, v53
	v_add_co_u32_e32 v52, vcc, s4, v128
	s_mov_b32 s4, 0x16000
	s_nop 0
	v_addc_co_u32_e32 v53, vcc, 0, v129, vcc
	v_cvt_pk_bf16_f32 v51, v54, v55
	global_store_dwordx4 v[52:53], v[48:51], off
	v_cvt_pk_bf16_f32 v40, v40, v41
	v_cvt_pk_bf16_f32 v41, v42, v43
	v_cvt_pk_bf16_f32 v42, v32, v33
	v_add_co_u32_e32 v32, vcc, s4, v128
	v_cvt_pk_bf16_f32 v43, v34, v35
	s_mov_b32 s4, 0x18000
	s_nop 0
	v_addc_co_u32_e32 v33, vcc, 0, v129, vcc
	global_store_dwordx4 v[32:33], v[40:43], off
	v_cvt_pk_bf16_f32 v32, v44, v45
	v_cvt_pk_bf16_f32 v33, v46, v47
	v_cvt_pk_bf16_f32 v34, v36, v37
	v_add_co_u32_e32 v36, vcc, s4, v128
	s_mov_b32 s4, 0x1a000
	s_nop 0
	v_addc_co_u32_e32 v37, vcc, 0, v129, vcc
	v_cvt_pk_bf16_f32 v35, v38, v39
	global_store_dwordx4 v[36:37], v[32:35], off
	v_cvt_pk_bf16_f32 v24, v24, v25
	v_cvt_pk_bf16_f32 v25, v26, v27
	v_cvt_pk_bf16_f32 v26, v16, v17
	v_add_co_u32_e32 v16, vcc, s4, v128
	v_cvt_pk_bf16_f32 v27, v18, v19
	s_mov_b32 s4, 0x1c000
	s_nop 0
	v_addc_co_u32_e32 v17, vcc, 0, v129, vcc
	global_store_dwordx4 v[16:17], v[24:27], off
	v_cvt_pk_bf16_f32 v16, v28, v29
	v_cvt_pk_bf16_f32 v17, v30, v31
	v_cvt_pk_bf16_f32 v18, v20, v21
	v_add_co_u32_e32 v20, vcc, s4, v128
	v_cvt_pk_bf16_f32 v19, v22, v23
	s_nop 1
	v_addc_co_u32_e32 v21, vcc, 0, v129, vcc
	global_store_dwordx4 v[20:21], v[16:19], off
	v_cvt_pk_bf16_f32 v12, v12, v13
	v_cvt_pk_bf16_f32 v13, v14, v15
	v_cvt_pk_bf16_f32 v14, v8, v9
	v_add_co_u32_e32 v8, vcc, 0x1e000, v128
	v_cvt_pk_bf16_f32 v15, v10, v11
	s_nop 1
	v_addc_co_u32_e32 v9, vcc, 0, v129, vcc
	global_store_dwordx4 v[8:9], v[12:15], off
	s_and_b64 vcc, exec, s[2:3]
	s_cbranch_vccz .LBB0_1257
	s_waitcnt vmcnt(0)
	s_cmpk_gt_u32 s24, 0xff
	s_cbranch_scc1 .LBB0_1264
	s_barrier

; #define G_STAGE(bufoff, gbase, o0, h64) do { \
;         __builtin_amdgcn_global_load_lds((const unsigned*)((const char*)(gbase) + (o0)), (LAS unsigned*)(lds + (bufoff) + ldsw), 16, 0, 0); \
;         __builtin_amdgcn_global_load_lds((const unsigned*)((const char*)(gbase) + (h64) + (o0)), (LAS unsigned*)(lds + (bufoff) + ldsw + 8192), 16, 0, 0); } while (0)
; #define G_LDA(dst, b, h) do { _Pragma("unroll") for (int m = 0; m < 4; ++m) _Pragma("unroll") for (int k = 0; k < 2; ++k) dst[m][k] = *(const LAS bf16x8*)(lds + G_SA(b, h) + aoff + m * 2048 + k * 1024); } while (0)
; #define G_LDB(dst, b, h) do { _Pragma("unroll") for (int n = 0; n < 2; ++n) _Pragma("unroll") for (int k = 0; k < 2; ++k) dst[n][k] = *(const LAS bf16x8*)(lds + G_SB(b, h) + boff + n * 2048 + k * 1024); } while (0)
; #define G_WAIT_L(n) asm volatile("s_waitcnt lgkmcnt(" #n ")" ::: "memory")
; #define G_BAR __builtin_amdgcn_s_barrier()
; #define G_SCHED __builtin_amdgcn_sched_barrier(0)
;     ...
;         for (int t = 0; t < nt; t += 2) {
;             const bool last = (t == nt - 2);
;             const char* a1 = cA + (size_t)(t + 1) * ckA;
;             const char* a2 = last ? nA : cA + (size_t)(t + 2) * ckA; const char* b2 = last ? nB : cB + (size_t)(t + 2) * kB;
;             const char* a3 = a2 + ckA; const char* b3 = b2 + kB;
;             G_LDB(B0, 0, 0); G_SCHED; G_LDA(At, 0, 0); G_STAGE(G_SA(1, 1), a1 + chA, cA0, qA);
;             G_WAIT_L(8); G_BAR; G_WAIT_L(0); G_MMA(0, 0, At, B0); G_BAR; G_SCHED;
;             G_LDB(B1, 0, 1); G_STAGE(G_SB(0, 0), b2, cB0, qB);
;             G_BAR; G_WAIT_L(0); G_MMA(0, 1, At, B1); G_BAR;
;             G_LDA(At, 0, 1); G_STAGE(G_SA(0, 0), a2, cA0, qA);
;             G_BAR; G_WAIT_L(0); G_MMA(1, 0, At, B0); G_BAR; G_SCHED;
.LBB0_1283:
	s_add_u32 s4, s2, 0xfffc0080
	s_addc_u32 s5, s3, -1
	s_add_i32 s25, 0, 0x10000
	v_add_u32_e32 v0, s25, v181
	ds_read_b128 v[136:139], v0
	ds_read_b128 v[140:143], v0 offset:1024
	ds_read_b128 v[144:147], v0 offset:2048
	ds_read_b128 v[148:151], v0 offset:3072
	s_cmp_eq_u32 s24, 12
	s_cselect_b32 s5, s19, s5
	s_cselect_b32 s4, s18, s4
	s_cselect_b32 s41, s21, s23
	s_cselect_b32 s40, s20, s22
	v_lshl_add_u64 v[184:185], s[2:3], 0, v[158:159]
	s_add_i32 m0, s29, 0xc000
	ds_read_b128 v[152:155], v182
	ds_read_b128 v[160:163], v182 offset:1024
	ds_read_b128 v[164:167], v182 offset:2048
	ds_read_b128 v[172:175], v182 offset:3072
	ds_read_b128 v[176:179], v182 offset:4096
	ds_read_b128 v[196:199], v182 offset:5120
	ds_read_b128 v[200:203], v182 offset:6144
	ds_read_b128 v[204:207], v182 offset:7168
	global_load_lds_dwordx4 v[184:185], off
	v_lshl_add_u64 v[184:185], v[184:185], 0, s[0:1]
	s_add_i32 m0, s29, 0xe000
	s_nop 0
	global_load_lds_dwordx4 v[184:185], off
	s_waitcnt lgkmcnt(8)
	s_barrier
	s_waitcnt lgkmcnt(0)
	s_waitcnt lgkmcnt(0)
	v_mfma_f32_16x16x32_bf16 v[132:135], v[136:139], v[152:155], v[132:135]
	v_mfma_f32_16x16x32_bf16 v[128:131], v[144:147], v[152:155], v[128:131]
	v_mfma_f32_16x16x32_bf16 v[116:119], v[136:139], v[164:167], v[116:119]
	v_mfma_f32_16x16x32_bf16 v[112:115], v[144:147], v[164:167], v[112:115]
	v_mfma_f32_16x16x32_bf16 v[100:103], v[136:139], v[176:179], v[100:103]
	v_mfma_f32_16x16x32_bf16 v[96:99], v[144:147], v[176:179], v[96:99]
	v_mfma_f32_16x16x32_bf16 v[84:87], v[136:139], v[200:203], v[84:87]
	v_mfma_f32_16x16x32_bf16 v[80:83], v[144:147], v[200:203], v[80:83]
	v_mfma_f32_16x16x32_bf16 v[132:135], v[140:143], v[160:163], v[132:135]
	v_mfma_f32_16x16x32_bf16 v[128:131], v[148:151], v[160:163], v[128:131]
	v_mfma_f32_16x16x32_bf16 v[116:119], v[140:143], v[172:175], v[116:119]
	v_mfma_f32_16x16x32_bf16 v[112:115], v[148:151], v[172:175], v[112:115]
	v_mfma_f32_16x16x32_bf16 v[100:103], v[140:143], v[196:199], v[100:103]
	v_mfma_f32_16x16x32_bf16 v[96:99], v[148:151], v[196:199], v[96:99]
	v_mfma_f32_16x16x32_bf16 v[84:87], v[140:143], v[204:207], v[84:87]
	v_mfma_f32_16x16x32_bf16 v[80:83], v[148:151], v[204:207], v[80:83]
	s_barrier
	s_add_i32 s44, 0, 0x14000
	s_add_i32 s25, s25, s27
	v_add_u32_e32 v0, s44, v181
	v_lshl_add_u64 v[184:185], s[40:41], 0, v[156:157]
	s_mov_b32 m0, s25
	ds_read_b128 v[208:211], v0
	ds_read_b128 v[212:215], v0 offset:1024
	ds_read_b128 v[216:219], v0 offset:2048
	ds_read_b128 v[220:223], v0 offset:3072
	global_load_lds_dwordx4 v[184:185], off
	v_lshl_add_u64 v[224:225], v[184:185], 0, s[0:1]
	s_add_i32 m0, s25, 0x2000
	s_nop 0
	global_load_lds_dwordx4 v[224:225], off
	s_barrier
	s_waitcnt lgkmcnt(0)
	s_waitcnt lgkmcnt(0)
	v_mfma_f32_16x16x32_bf16 v[124:127], v[208:211], v[152:155], v[124:127]
	v_mfma_f32_16x16x32_bf16 v[120:123], v[216:219], v[152:155], v[120:123]
	v_mfma_f32_16x16x32_bf16 v[108:111], v[208:211], v[164:167], v[108:111]
	v_mfma_f32_16x16x32_bf16 v[104:107], v[216:219], v[164:167], v[104:107]
	v_mfma_f32_16x16x32_bf16 v[92:95], v[208:211], v[176:179], v[92:95]
	v_mfma_f32_16x16x32_bf16 v[88:91], v[216:219], v[176:179], v[88:91]
	v_mfma_f32_16x16x32_bf16 v[76:79], v[208:211], v[200:203], v[76:79]
	v_mfma_f32_16x16x32_bf16 v[72:75], v[216:219], v[200:203], v[72:75]
	v_mfma_f32_16x16x32_bf16 v[124:127], v[212:215], v[160:163], v[124:127]
	v_mfma_f32_16x16x32_bf16 v[120:123], v[220:223], v[160:163], v[120:123]
	v_mfma_f32_16x16x32_bf16 v[108:111], v[212:215], v[172:175], v[108:111]
	v_mfma_f32_16x16x32_bf16 v[104:107], v[220:223], v[172:175], v[104:107]
	v_mfma_f32_16x16x32_bf16 v[92:95], v[212:215], v[196:199], v[92:95]
	v_mfma_f32_16x16x32_bf16 v[88:91], v[220:223], v[196:199], v[88:91]
	v_mfma_f32_16x16x32_bf16 v[76:79], v[212:215], v[204:207], v[76:79]
	v_mfma_f32_16x16x32_bf16 v[72:75], v[220:223], v[204:207], v[72:75]
	s_mov_b32 m0, s29
	v_lshl_add_u64 v[224:225], s[4:5], 0, v[2:3]
	s_barrier
	ds_read_b128 v[152:155], v182 offset:16384
	ds_read_b128 v[160:163], v182 offset:17408
	ds_read_b128 v[164:167], v182 offset:18432
	ds_read_b128 v[172:175], v182 offset:19456
	ds_read_b128 v[176:179], v182 offset:20480
	ds_read_b128 v[196:199], v182 offset:21504
	ds_read_b128 v[200:203], v182 offset:22528
	ds_read_b128 v[204:207], v182 offset:23552
	global_load_lds_dwordx4 v[224:225], off
	v_lshl_add_u64 v[226:227], v[224:225], 0, s[0:1]
	s_mov_b32 m0, s30
	s_nop 0
	global_load_lds_dwordx4 v[226:227], off
	s_barrier
	s_waitcnt lgkmcnt(0)
	s_waitcnt lgkmcnt(0)
	v_mfma_f32_16x16x32_bf16 v[68:71], v[136:139], v[152:155], v[68:71]
	v_mfma_f32_16x16x32_bf16 v[64:67], v[144:147], v[152:155], v[64:67]
	v_mfma_f32_16x16x32_bf16 v[52:55], v[136:139], v[164:167], v[52:55]
	v_mfma_f32_16x16x32_bf16 v[48:51], v[144:147], v[164:167], v[48:51]
	v_mfma_f32_16x16x32_bf16 v[36:39], v[136:139], v[176:179], v[36:39]
	v_mfma_f32_16x16x32_bf16 v[32:35], v[144:147], v[176:179], v[32:35]
	v_mfma_f32_16x16x32_bf16 v[20:23], v[136:139], v[200:203], v[20:23]
	v_mfma_f32_16x16x32_bf16 v[16:19], v[144:147], v[200:203], v[16:19]
	v_mfma_f32_16x16x32_bf16 v[68:71], v[140:143], v[160:163], v[68:71]
	v_mfma_f32_16x16x32_bf16 v[64:67], v[148:151], v[160:163], v[64:67]
	v_mfma_f32_16x16x32_bf16 v[52:55], v[140:143], v[172:175], v[52:55]
	v_mfma_f32_16x16x32_bf16 v[48:51], v[148:151], v[172:175], v[48:51]
	v_mfma_f32_16x16x32_bf16 v[36:39], v[140:143], v[196:199], v[36:39]
	v_mfma_f32_16x16x32_bf16 v[32:35], v[148:151], v[196:199], v[32:35]
	v_mfma_f32_16x16x32_bf16 v[20:23], v[140:143], v[204:207], v[20:23]
	v_mfma_f32_16x16x32_bf16 v[16:19], v[148:151], v[204:207], v[16:19]
	s_barrier
; #define G_STAGE(bufoff, gbase, o0, h64) do { \
;         __builtin_amdgcn_global_load_lds((const unsigned*)((const char*)(gbase) + (o0)), (LAS unsigned*)(lds + (bufoff) + ldsw), 16, 0, 0); \
;         __builtin_amdgcn_global_load_lds((const unsigned*)((const char*)(gbase) + (h64) + (o0)), (LAS unsigned*)(lds + (bufoff) + ldsw + 8192), 16, 0, 0); } while (0)
; #define G_LDA(dst, b, h) do { _Pragma("unroll") for (int m = 0; m < 4; ++m) _Pragma("unroll") for (int k = 0; k < 2; ++k) dst[m][k] = *(const LAS bf16x8*)(lds + G_SA(b, h) + aoff + m * 2048 + k * 1024); } while (0)
; #define G_LDB(dst, b, h) do { _Pragma("unroll") for (int n = 0; n < 2; ++n) _Pragma("unroll") for (int k = 0; k < 2; ++k) dst[n][k] = *(const LAS bf16x8*)(lds + G_SB(b, h) + boff + n * 2048 + k * 1024); } while (0)
; #define G_WAIT_V(n) asm volatile("s_waitcnt vmcnt(" #n ")" ::: "memory")
; #define G_WAIT_L(n) asm volatile("s_waitcnt lgkmcnt(" #n ")" ::: "memory")
; #define G_BAR __builtin_amdgcn_s_barrier()
; #define G_SCHED __builtin_amdgcn_sched_barrier(0)
;     ...
;             G_STAGE(G_SB(0, 1), b2 + chB, cB0, qB);
;             G_WAIT_V(6); G_BAR; G_MMA(1, 1, At, B1); G_BAR;
;             G_LDB(B0, 1, 0); G_SCHED; G_LDA(At, 1, 0); G_STAGE(G_SA(0, 1), a2 + chA, cA0, qA);
;             G_WAIT_L(8); G_BAR; G_WAIT_L(0); G_MMA(0, 0, At, B0); G_BAR; G_SCHED;
;             G_LDB(B1, 1, 1); G_STAGE(G_SB(1, 0), b3, cB0, qB);
;             G_BAR; G_WAIT_L(0); G_MMA(0, 1, At, B1); G_BAR;
	s_add_i32 s4, s44, s27
	v_lshl_add_u64 v[136:137], v[184:185], 0, s[54:55]
	s_mov_b32 m0, s4
	s_nop 0
	global_load_lds_dwordx4 v[136:137], off
	v_lshl_add_u64 v[136:137], v[184:185], 0, s[58:59]
	s_add_i32 m0, s4, 0x2000
	s_nop 0
	global_load_lds_dwordx4 v[136:137], off
	s_waitcnt vmcnt(6)
	s_barrier
	v_mfma_f32_16x16x32_bf16 v[60:63], v[208:211], v[152:155], v[60:63]
	v_mfma_f32_16x16x32_bf16 v[56:59], v[216:219], v[152:155], v[56:59]
	v_mfma_f32_16x16x32_bf16 v[44:47], v[208:211], v[164:167], v[44:47]
	v_mfma_f32_16x16x32_bf16 v[40:43], v[216:219], v[164:167], v[40:43]
	v_mfma_f32_16x16x32_bf16 v[28:31], v[208:211], v[176:179], v[28:31]
	v_mfma_f32_16x16x32_bf16 v[24:27], v[216:219], v[176:179], v[24:27]
	v_mfma_f32_16x16x32_bf16 v[12:15], v[208:211], v[200:203], v[12:15]
	v_mfma_f32_16x16x32_bf16 v[8:11], v[216:219], v[200:203], v[8:11]
	v_mfma_f32_16x16x32_bf16 v[60:63], v[212:215], v[160:163], v[60:63]
	v_mfma_f32_16x16x32_bf16 v[56:59], v[220:223], v[160:163], v[56:59]
	v_mfma_f32_16x16x32_bf16 v[44:47], v[212:215], v[172:175], v[44:47]
	v_mfma_f32_16x16x32_bf16 v[40:43], v[220:223], v[172:175], v[40:43]
	v_mfma_f32_16x16x32_bf16 v[28:31], v[212:215], v[196:199], v[28:31]
	v_mfma_f32_16x16x32_bf16 v[24:27], v[220:223], v[196:199], v[24:27]
	v_mfma_f32_16x16x32_bf16 v[12:15], v[212:215], v[204:207], v[12:15]
	v_mfma_f32_16x16x32_bf16 v[8:11], v[220:223], v[204:207], v[8:11]
	s_add_i32 s4, 0, 0x18000
	v_add_u32_e32 v0, s4, v181
	s_barrier
	ds_read_b128 v[136:139], v0
	ds_read_b128 v[140:143], v0 offset:1024
	ds_read_b128 v[144:147], v0 offset:2048
	ds_read_b128 v[148:151], v0 offset:3072
	s_mov_b32 m0, s31
	v_lshl_add_u64 v[208:209], v[224:225], 0, s[54:55]
	ds_read_b128 v[152:155], v182 offset:32768
	ds_read_b128 v[160:163], v182 offset:33792
	ds_read_b128 v[164:167], v182 offset:34816
	ds_read_b128 v[172:175], v182 offset:35840
	ds_read_b128 v[176:179], v182 offset:36864
	ds_read_b128 v[196:199], v182 offset:37888
	ds_read_b128 v[200:203], v182 offset:38912
	ds_read_b128 v[204:207], v182 offset:39936
	global_load_lds_dwordx4 v[208:209], off
	v_lshl_add_u64 v[208:209], v[224:225], 0, s[58:59]
	s_mov_b32 m0, s34
	s_nop 0
	global_load_lds_dwordx4 v[208:209], off
	s_waitcnt lgkmcnt(8)
	s_barrier
	s_waitcnt lgkmcnt(0)
	s_waitcnt lgkmcnt(0)
	v_mfma_f32_16x16x32_bf16 v[132:135], v[136:139], v[152:155], v[132:135]
	v_mfma_f32_16x16x32_bf16 v[128:131], v[144:147], v[152:155], v[128:131]
	v_mfma_f32_16x16x32_bf16 v[116:119], v[136:139], v[164:167], v[116:119]
	v_mfma_f32_16x16x32_bf16 v[112:115], v[144:147], v[164:167], v[112:115]
	v_mfma_f32_16x16x32_bf16 v[100:103], v[136:139], v[176:179], v[100:103]
	v_mfma_f32_16x16x32_bf16 v[96:99], v[144:147], v[176:179], v[96:99]
	v_mfma_f32_16x16x32_bf16 v[84:87], v[136:139], v[200:203], v[84:87]
	v_mfma_f32_16x16x32_bf16 v[80:83], v[144:147], v[200:203], v[80:83]
	v_mfma_f32_16x16x32_bf16 v[132:135], v[140:143], v[160:163], v[132:135]
	v_mfma_f32_16x16x32_bf16 v[128:131], v[148:151], v[160:163], v[128:131]
	v_mfma_f32_16x16x32_bf16 v[116:119], v[140:143], v[172:175], v[116:119]
	v_mfma_f32_16x16x32_bf16 v[112:115], v[148:151], v[172:175], v[112:115]
	v_mfma_f32_16x16x32_bf16 v[100:103], v[140:143], v[196:199], v[100:103]
	v_mfma_f32_16x16x32_bf16 v[96:99], v[148:151], v[196:199], v[96:99]
	v_mfma_f32_16x16x32_bf16 v[84:87], v[140:143], v[204:207], v[84:87]
	v_mfma_f32_16x16x32_bf16 v[80:83], v[148:151], v[204:207], v[80:83]
	s_barrier
	s_add_i32 s5, 0, 0x1c000
	s_add_i32 s4, s4, s27
	v_add_u32_e32 v0, s5, v181
	v_lshl_add_u64 v[226:227], v[184:185], 0, s[46:47]
	s_mov_b32 m0, s4
	ds_read_b128 v[208:211], v0
	ds_read_b128 v[212:215], v0 offset:1024
	ds_read_b128 v[216:219], v0 offset:2048
	ds_read_b128 v[220:223], v0 offset:3072
	global_load_lds_dwordx4 v[226:227], off
	v_lshl_add_u64 v[226:227], v[184:185], 0, s[62:63]
	s_add_i32 m0, s4, 0x2000
	s_nop 0
	global_load_lds_dwordx4 v[226:227], off
	s_barrier
	s_waitcnt lgkmcnt(0)
	s_waitcnt lgkmcnt(0)
	v_mfma_f32_16x16x32_bf16 v[124:127], v[208:211], v[152:155], v[124:127]
	v_mfma_f32_16x16x32_bf16 v[120:123], v[216:219], v[152:155], v[120:123]
	v_mfma_f32_16x16x32_bf16 v[108:111], v[208:211], v[164:167], v[108:111]
	v_mfma_f32_16x16x32_bf16 v[104:107], v[216:219], v[164:167], v[104:107]
	v_mfma_f32_16x16x32_bf16 v[92:95], v[208:211], v[176:179], v[92:95]
	v_mfma_f32_16x16x32_bf16 v[88:91], v[216:219], v[176:179], v[88:91]
	v_mfma_f32_16x16x32_bf16 v[76:79], v[208:211], v[200:203], v[76:79]
	v_mfma_f32_16x16x32_bf16 v[72:75], v[216:219], v[200:203], v[72:75]
	v_mfma_f32_16x16x32_bf16 v[124:127], v[212:215], v[160:163], v[124:127]
	v_mfma_f32_16x16x32_bf16 v[120:123], v[220:223], v[160:163], v[120:123]
	v_mfma_f32_16x16x32_bf16 v[108:111], v[212:215], v[172:175], v[108:111]
	v_mfma_f32_16x16x32_bf16 v[104:107], v[220:223], v[172:175], v[104:107]
	v_mfma_f32_16x16x32_bf16 v[92:95], v[212:215], v[196:199], v[92:95]
	v_mfma_f32_16x16x32_bf16 v[88:91], v[220:223], v[196:199], v[88:91]
	v_mfma_f32_16x16x32_bf16 v[76:79], v[212:215], v[204:207], v[76:79]
	v_mfma_f32_16x16x32_bf16 v[72:75], v[220:223], v[204:207], v[72:75]
	s_mov_b32 m0, s35
	v_lshl_add_u64 v[226:227], v[224:225], 0, s[46:47]
	s_barrier
	ds_read_b128 v[152:155], v182 offset:49152
	ds_read_b128 v[160:163], v182 offset:50176
	ds_read_b128 v[164:167], v182 offset:51200
	ds_read_b128 v[172:175], v182 offset:52224
	ds_read_b128 v[176:179], v182 offset:53248
	ds_read_b128 v[196:199], v182 offset:54272
	ds_read_b128 v[200:203], v182 offset:55296
	ds_read_b128 v[204:207], v182 offset:56320
	global_load_lds_dwordx4 v[226:227], off
	v_lshl_add_u64 v[224:225], v[224:225], 0, s[62:63]
	s_mov_b32 m0, s36
	s_nop 0
	global_load_lds_dwordx4 v[224:225], off
	s_barrier
; __device__ __forceinline__ float sigmoidf_(float v) { return __builtin_amdgcn_rcpf(1.0f + __expf(-v)); }
; __device__ __forceinline__ void unpack8(const u32x4 w, f32x4& a, f32x4& b) { a[0] = bf_lo(w.x); a[1] = bf_hi(w.x); a[2] = bf_lo(w.y); a[3] = bf_hi(w.y); b[0] = bf_lo(w.z); b[1] = bf_hi(w.z); b[2] = bf_lo(w.w); b[3] = bf_hi(w.w); }
; #define G_WAIT_V(n) asm volatile("s_waitcnt vmcnt(" #n ")" ::: "memory")
; #define G_WAIT_L(n) asm volatile("s_waitcnt lgkmcnt(" #n ")" ::: "memory")
; #define G_BAR __builtin_amdgcn_s_barrier()
;     template <int KIND> __device__ __forceinline__ void run(f32x4 (&acc)[2][2][4][2], const Unit& u, int tid_in) const {
;     ...
;         if constexpr (KIND == K_PLE) {
;             const bf16_t* xsrc = mg; float rs[8]; get_rs(u, wr, fr, rs);
; #pragma unroll
;             for (int ai = 0; ai < 2; ++ai)
; #pragma unroll
;                 for (int mh = 0; mh < 2; ++mh) { u32x4 xv[2][2], pv[2][2];
; #pragma unroll
;                     for (int ml = 0; ml < 2; ++ml) { const int m = mh * 2 + ml; int row = rbase + ai * 128 + m * 16; asm volatile("" : "+v"(row));
; #pragma unroll
;                         for (int bj = 0; bj < 2; ++bj) { xv[ml][bj] = *(const u32x4*)(xsrc + (size_t)row * 1024 + u.pn * 256 + bj * 128 + cl); pv[ml][bj] = scr[((ai * 4 + m) * 2 + bj) * 512 + tid]; } }
; #pragma unroll
;                     for (int ml = 0; ml < 2; ++ml) { const int m = mh * 2 + ml; int row = rbase + ai * 128 + m * 16; asm volatile("" : "+v"(row)); float ss = 0.f; const float r = rs[ai * 4 + m];
; #pragma unroll
;                         for (int bj = 0; bj < 2; ++bj) { const size_t off = (size_t)row * 1024 + u.pn * 256 + bj * 128 + cl; f32x4 a = acc[ai][bj][m][0], b = acc[ai][bj][m][1], p0, p1, x0, x1;
;                             unpack8(pv[ml][bj], p0, p1); unpack8(xv[ml][bj], x0, x1);
; #pragma unroll
;                             for (int j = 0; j < 4; ++j) { a[j] = sigmoidf_(a[j] * r) * p0[j]; b[j] = sigmoidf_(b[j] * r) * p1[j]; }
;     ...
;             G_BAR; G_WAIT_L(0); G_MMA(0, 1, At, B1); G_BAR;
;             G_LDA(At, 1, 1); G_STAGE(G_SA(1, 0), a3, cA0, qA);
;             G_BAR; G_WAIT_L(0); G_MMA(1, 0, At, B0); G_BAR; G_SCHED;
;             G_STAGE(G_SB(1, 1), b3 + chB, cB0, qB);
;             G_WAIT_V(6); G_BAR; G_MMA(1, 1, At, B1); G_BAR;
;         }
;         E.template run<cs.kind>(acc, cur, tid);
;         if (!has_next) break;
	s_waitcnt lgkmcnt(0)
	s_waitcnt lgkmcnt(0)
	v_mfma_f32_16x16x32_bf16 v[68:71], v[136:139], v[152:155], v[68:71]
	v_mfma_f32_16x16x32_bf16 v[64:67], v[144:147], v[152:155], v[64:67]
	v_mfma_f32_16x16x32_bf16 v[52:55], v[136:139], v[164:167], v[52:55]
	v_mfma_f32_16x16x32_bf16 v[48:51], v[144:147], v[164:167], v[48:51]
	v_mfma_f32_16x16x32_bf16 v[36:39], v[136:139], v[176:179], v[36:39]
	v_mfma_f32_16x16x32_bf16 v[32:35], v[144:147], v[176:179], v[32:35]
	v_mfma_f32_16x16x32_bf16 v[20:23], v[136:139], v[200:203], v[20:23]
	v_mfma_f32_16x16x32_bf16 v[16:19], v[144:147], v[200:203], v[16:19]
	v_mfma_f32_16x16x32_bf16 v[68:71], v[140:143], v[160:163], v[68:71]
	v_mfma_f32_16x16x32_bf16 v[64:67], v[148:151], v[160:163], v[64:67]
	v_mfma_f32_16x16x32_bf16 v[52:55], v[140:143], v[172:175], v[52:55]
	v_mfma_f32_16x16x32_bf16 v[48:51], v[148:151], v[172:175], v[48:51]
	v_mfma_f32_16x16x32_bf16 v[36:39], v[140:143], v[196:199], v[36:39]
	v_mfma_f32_16x16x32_bf16 v[32:35], v[148:151], v[196:199], v[32:35]
	v_mfma_f32_16x16x32_bf16 v[20:23], v[140:143], v[204:207], v[20:23]
	v_mfma_f32_16x16x32_bf16 v[16:19], v[148:151], v[204:207], v[16:19]
	s_barrier
	s_add_i32 s4, s5, s27
	v_lshl_add_u64 v[136:137], v[184:185], 0, s[64:65]
	s_mov_b32 m0, s4
	s_nop 0
	global_load_lds_dwordx4 v[136:137], off
	v_lshl_add_u64 v[136:137], v[184:185], 0, s[66:67]
	s_add_i32 m0, s4, 0x2000
	s_nop 0
	global_load_lds_dwordx4 v[136:137], off
	s_waitcnt vmcnt(6)
	s_barrier
	v_mfma_f32_16x16x32_bf16 v[60:63], v[208:211], v[152:155], v[60:63]
	v_mfma_f32_16x16x32_bf16 v[56:59], v[216:219], v[152:155], v[56:59]
	v_mfma_f32_16x16x32_bf16 v[44:47], v[208:211], v[164:167], v[44:47]
	v_mfma_f32_16x16x32_bf16 v[40:43], v[216:219], v[164:167], v[40:43]
	v_mfma_f32_16x16x32_bf16 v[28:31], v[208:211], v[176:179], v[28:31]
	v_mfma_f32_16x16x32_bf16 v[24:27], v[216:219], v[176:179], v[24:27]
	v_mfma_f32_16x16x32_bf16 v[12:15], v[208:211], v[200:203], v[12:15]
	v_mfma_f32_16x16x32_bf16 v[8:11], v[216:219], v[200:203], v[8:11]
	v_mfma_f32_16x16x32_bf16 v[60:63], v[212:215], v[160:163], v[60:63]
	v_mfma_f32_16x16x32_bf16 v[56:59], v[220:223], v[160:163], v[56:59]
	v_mfma_f32_16x16x32_bf16 v[44:47], v[212:215], v[172:175], v[44:47]
	v_mfma_f32_16x16x32_bf16 v[40:43], v[220:223], v[172:175], v[40:43]
	v_mfma_f32_16x16x32_bf16 v[28:31], v[212:215], v[196:199], v[28:31]
	v_mfma_f32_16x16x32_bf16 v[24:27], v[220:223], v[196:199], v[24:27]
	v_mfma_f32_16x16x32_bf16 v[12:15], v[212:215], v[204:207], v[12:15]
	v_mfma_f32_16x16x32_bf16 v[8:11], v[220:223], v[204:207], v[8:11]
	s_add_i32 s24, s24, 2
	s_add_u32 s2, s2, 0x100
	s_addc_u32 s3, s3, 0
	s_add_u32 s22, s22, 0x100
	s_addc_u32 s23, s23, 0
	s_cmp_gt_u32 s24, 13
	s_barrier
	s_cbranch_scc0 .LBB0_1283
	v_mov_b32_e32 v136, v180
	s_lshl_b32 s2, s33, 17
	v_readfirstlane_b32 s4, v136
	s_bfe_u32 s53, s4, 0x20006
	s_and_b32 s2, s2, 0x20000
	s_add_u32 s2, s43, s2
	s_addc_u32 s3, s50, 0
	s_lshl_b32 s5, s7, 8
	s_ashr_i32 s7, s4, 2
	s_andn2_b32 s7, s7, 63
	s_add_i32 s7, s7, s5
	s_lshl_b32 s5, s33, 10
	s_add_i32 s5, s5, 0
	s_and_b32 s4, s4, 0xffffff00
	v_and_b32_e32 v0, 15, v136
	s_add_i32 s5, s5, s4
	v_or_b32_e32 v183, s7, v0
	v_lshl_add_u32 v0, v0, 2, s5
	v_add_u32_e32 v0, 0x20010, v0
	v_mov_b32_e32 v138, v183
	v_bfe_u32 v140, v136, 4, 2
	ds_read2_b32 v[176:177], v0 offset1:16
	ds_read2_b32 v[172:173], v0 offset0:32 offset1:48
	ds_read2_b32 v[166:167], v0 offset0:128 offset1:144
	ds_read2_b32 v[160:161], v0 offset0:160 offset1:176
	s_lshl_b32 s22, s6, 8
	v_ashrrev_i32_e32 v139, 31, v138
	v_lshlrev_b32_e32 v137, 3, v140
	v_lshlrev_b64 v[138:139], 11, v[138:139]
	s_ashr_i32 s23, s22, 31
	v_lshl_or_b32 v162, s53, 5, v137
	v_lshl_add_u64 v[138:139], s[8:9], 0, v[138:139]
	s_lshl_b64 s[24:25], s[22:23], 1
	v_lshl_add_u64 v[138:139], v[138:139], 0, s[24:25]
	v_lshlrev_b32_e32 v0, 1, v162
	v_ashrrev_i32_e32 v137, 31, v136
	v_lshl_add_u64 v[138:139], v[138:139], 0, v[0:1]
	v_lshl_add_u64 v[164:165], v[136:137], 4, s[2:3]
	global_load_dwordx4 v[196:199], v[138:139], off
	global_load_dwordx4 v[200:203], v[164:165], off
	s_movk_i32 s2, 0x2000
	v_add_co_u32_e32 v136, vcc, s2, v164
	v_cmp_eq_u32_e64 s[40:41], 0, v140
	s_nop 0
	v_addc_co_u32_e32 v137, vcc, 0, v165, vcc
	global_load_dwordx4 v[204:207], v[138:139], off offset:256
	global_load_dwordx4 v[152:155], v[136:137], off
	v_add_co_u32_e32 v140, vcc, s49, v164
	v_or_b32_e32 v174, 16, v183
	s_nop 0
	v_addc_co_u32_e32 v141, vcc, 0, v165, vcc
	s_movk_i32 s2, 0x6000
	v_mov_b32_e32 v148, v174
	s_waitcnt lgkmcnt(0)
	v_mul_f32_e32 v132, v132, v176
	v_mul_f32_e32 v133, v133, v176
	v_add_co_u32_e32 v142, vcc, s2, v164
	v_mul_f32_e32 v132, 0xbfb8aa3b, v132
	v_mul_f32_e32 v133, 0xbfb8aa3b, v133
	v_ashrrev_i32_e32 v149, 31, v148
	v_addc_co_u32_e32 v143, vcc, 0, v165, vcc
	global_load_dwordx4 v[144:147], v[140:141], off
	global_load_dwordx4 v[136:139], v[142:143], off
	v_exp_f32_e32 v140, v132
	v_exp_f32_e32 v195, v133
	v_lshlrev_b64 v[132:133], 11, v[148:149]
	v_lshl_add_u64 v[132:133], s[8:9], 0, v[132:133]
	v_mul_f32_e32 v128, v128, v176
	v_lshl_add_u64 v[132:133], v[132:133], 0, s[24:25]
	v_mul_f32_e32 v128, 0xbfb8aa3b, v128
	v_lshl_add_u64 v[132:133], v[132:133], 0, v[0:1]
	v_exp_f32_e32 v175, v128
	v_add_f32_e32 v128, 1.0, v140
	global_load_dwordx4 v[148:151], v[132:133], off
	global_load_dwordx4 v[140:143], v[132:133], off offset:256
	v_mul_f32_e32 v129, v129, v176
	v_add_f32_e32 v175, 1.0, v175
	v_mul_f32_e32 v129, 0xbfb8aa3b, v129
	v_rcp_f32_e32 v212, v175
	v_add_f32_e32 v175, 1.0, v195
	v_exp_f32_e32 v195, v129
	v_mul_f32_e32 v134, v134, v176
	v_mul_f32_e32 v134, 0xbfb8aa3b, v134
	v_mul_f32_e32 v130, v130, v176
	v_rcp_f32_e32 v129, v175
	v_add_f32_e32 v175, 1.0, v195
	v_exp_f32_e32 v134, v134
	v_mul_f32_e32 v130, 0xbfb8aa3b, v130
	v_rcp_f32_e32 v213, v175
	v_exp_f32_e32 v175, v130
	v_mul_f32_e32 v130, v135, v176
	v_mul_f32_e32 v130, 0xbfb8aa3b, v130
	v_mul_f32_e32 v131, v131, v176
	v_add_f32_e32 v134, 1.0, v134
	v_exp_f32_e32 v135, v130
	v_mul_f32_e32 v131, 0xbfb8aa3b, v131
	v_rcp_f32_e32 v130, v134
	v_add_f32_e32 v134, 1.0, v175
	v_exp_f32_e32 v175, v131
	v_mov_b32_e32 v178, v183
	v_add_f32_e32 v135, 1.0, v135
	v_mov_b64_e32 v[184:185], s[10:11]
	v_rcp_f32_e32 v128, v128
	v_ashrrev_i32_e32 v179, 31, v178
	v_rcp_f32_e32 v131, v135
	v_add_f32_e32 v135, 1.0, v175
	v_mad_i64_i32 v[132:133], s[2:3], v178, s76, v[184:185]
	v_lshlrev_b64 v[184:185], 11, v[178:179]
	v_rcp_f32_e32 v134, v134
	v_rcp_f32_e32 v135, v135
	v_lshl_add_u64 v[184:185], s[12:13], 0, v[184:185]
	v_lshl_add_u64 v[184:185], v[184:185], 0, s[24:25]
	v_lshl_add_u64 v[184:185], v[184:185], 0, v[0:1]
	v_mov_b32_e32 v163, v1
	v_mul_f32_e32 v124, v124, v176
	s_waitcnt vmcnt(0)
; __device__ __forceinline__ float sigmoidf_(float v) { return __builtin_amdgcn_rcpf(1.0f + __expf(-v)); }
; __device__ __forceinline__ u32x4 pack8(const f32x4 a, const f32x4 b) { u32x4 w; w.x = cvt_pk_bf16(a[0], a[1]); w.y = cvt_pk_bf16(a[2], a[3]); w.z = cvt_pk_bf16(b[0], b[1]); w.w = cvt_pk_bf16(b[2], b[3]); return w; }
;     template <int KIND> __device__ __forceinline__ void run(f32x4 (&acc)[2][2][4][2], const Unit& u, int tid_in) const {
;     ...
;                     for (int ml = 0; ml < 2; ++ml) { const int m = mh * 2 + ml; int row = rbase + ai * 128 + m * 16; asm volatile("" : "+v"(row));
; #pragma unroll
;                         for (int bj = 0; bj < 2; ++bj) { xv[ml][bj] = *(const u32x4*)(xsrc + (size_t)row * 1024 + u.pn * 256 + bj * 128 + cl); pv[ml][bj] = scr[((ai * 4 + m) * 2 + bj) * 512 + tid]; } }
; #pragma unroll
;                     for (int ml = 0; ml < 2; ++ml) { const int m = mh * 2 + ml; int row = rbase + ai * 128 + m * 16; asm volatile("" : "+v"(row)); float ss = 0.f; const float r = rs[ai * 4 + m];
; #pragma unroll
;                         for (int bj = 0; bj < 2; ++bj) { const size_t off = (size_t)row * 1024 + u.pn * 256 + bj * 128 + cl; f32x4 a = acc[ai][bj][m][0], b = acc[ai][bj][m][1], p0, p1, x0, x1;
;                             unpack8(pv[ml][bj], p0, p1); unpack8(xv[ml][bj], x0, x1);
; #pragma unroll
;                             for (int j = 0; j < 4; ++j) { a[j] = sigmoidf_(a[j] * r) * p0[j]; b[j] = sigmoidf_(b[j] * r) * p1[j]; }
;                             const f32x4 o0 = x0 + a, o1 = x1 + b;
;                             *(u32x4*)(xb0 + off) = pack8(o0, o1);
;                             { u32x2 w8; w8.x = pack4_fp8(o0[0], o0[1], o0[2], o0[3]); w8.y = pack4_fp8(o1[0], o1[1], o1[2], o1[3]); *(u32x2*)((unsigned char*)zb + (size_t)row * (ZW * 2) + u.pn * 256 + bj * 128 + cl) = w8; }
;                             ss += (o0[0] * o0[0] + o0[1] * o0[1]) + (o0[2] * o0[2] + o0[3] * o0[3]) + (o1[0] * o1[0] + o1[1] * o1[1]) + (o1[2] * o1[2] + o1[3] * o1[3]); }
;                         ss += __shfl_xor(ss, 16); ss += __shfl_xor(ss, 32);
;                         if (fq == 0) ssq0[((size_t)u.pn * T_TOK + row) * 4 + wc] = ss; }
	v_lshlrev_b32_e32 v208, 16, v196
	v_and_b32_e32 v209, 0xffff0000, v196
	v_lshlrev_b32_e32 v196, 16, v197
	v_and_b32_e32 v197, 0xffff0000, v197
	v_lshlrev_b32_e32 v214, 16, v200
	v_and_b32_e32 v215, 0xffff0000, v200
	v_lshlrev_b32_e32 v200, 16, v201
	v_and_b32_e32 v201, 0xffff0000, v201
	v_lshlrev_b32_e32 v210, 16, v198
	v_and_b32_e32 v211, 0xffff0000, v198
	v_lshlrev_b32_e32 v198, 16, v199
	v_and_b32_e32 v199, 0xffff0000, v199
	v_lshlrev_b32_e32 v216, 16, v202
	v_and_b32_e32 v217, 0xffff0000, v202
	v_lshlrev_b32_e32 v202, 16, v203
	v_and_b32_e32 v203, 0xffff0000, v203
	v_pk_fma_f32 v[196:197], v[130:131], v[200:201], v[196:197]
	v_pk_fma_f32 v[200:201], v[128:129], v[214:215], v[208:209]
	v_pk_fma_f32 v[134:135], v[134:135], v[202:203], v[198:199]
	v_cvt_pk_bf16_f32 v128, v200, v201
	v_cvt_pk_bf16_f32 v129, v196, v197
	v_pk_fma_f32 v[198:199], v[212:213], v[216:217], v[210:211]
	v_mul_f32_e32 v0, v201, v201
	v_cvt_pk_bf16_f32 v130, v198, v199
	v_cvt_pk_bf16_f32 v131, v134, v135
	global_store_dwordx4 v[184:185], v[128:131], off
	v_mul_f32_e32 v124, 0xbfb8aa3b, v124
	v_mul_f32_e32 v120, v120, v176
	v_lshl_add_u64 v[128:129], v[132:133], 0, s[22:23]
	v_lshl_add_u64 v[130:131], v[128:129], 0, v[162:163]
	v_mul_f32_e32 v128, v197, v197
	v_fmac_f32_e32 v0, v200, v200
	v_fmac_f32_e32 v128, v196, v196
	v_exp_f32_e32 v124, v124
	v_mul_f32_e32 v120, 0xbfb8aa3b, v120
	v_mul_f32_e32 v122, v122, v176
	v_mov_b32_e32 v203, v1
	v_add_f32_e32 v0, v0, v128
	v_mul_f32_e32 v128, v199, v199
	v_exp_f32_e32 v175, v120
	v_mul_f32_e32 v122, 0xbfb8aa3b, v122
	v_cvt_pk_fp8_f32 v203, v198, v199
	v_fmac_f32_e32 v128, v198, v198
	v_mul_f32_e32 v120, v125, v176
	v_lshlrev_b32_e32 v198, 16, v152
	v_and_b32_e32 v199, 0xffff0000, v152
	v_mul_f32_e32 v126, v126, v176
	v_exp_f32_e32 v152, v122
	v_mul_f32_e32 v122, v127, v176
	v_mul_f32_e32 v120, 0xbfb8aa3b, v120
	v_mul_f32_e32 v121, v121, v176
	v_mul_f32_e32 v126, 0xbfb8aa3b, v126
	v_mul_f32_e32 v122, 0xbfb8aa3b, v122
	v_add_f32_e32 v124, 1.0, v124
	v_exp_f32_e32 v125, v120
	v_mul_f32_e32 v121, 0xbfb8aa3b, v121
	v_exp_f32_e32 v126, v126
	v_exp_f32_e32 v127, v122
	v_rcp_f32_e32 v120, v124
	v_add_f32_e32 v124, 1.0, v175
	v_exp_f32_e32 v175, v121
	v_mul_f32_e32 v123, v123, v176
	v_mov_b32_e32 v202, v1
	v_mul_f32_e32 v123, 0xbfb8aa3b, v123
	v_cvt_pk_fp8_f32 v202, v200, v201
	v_add_f32_e32 v125, 1.0, v125
	v_lshlrev_b32_e32 v200, 16, v154
	v_and_b32_e32 v201, 0xffff0000, v154
	v_add_f32_e32 v126, 1.0, v126
	v_add_f32_e32 v127, 1.0, v127
	v_exp_f32_e32 v154, v123
	v_rcp_f32_e32 v121, v125
	v_add_f32_e32 v125, 1.0, v175
	v_rcp_f32_e32 v122, v126
	v_rcp_f32_e32 v123, v127
	v_add_f32_e32 v0, v128, v0
	v_mul_f32_e32 v128, v135, v135
	v_rcp_f32_e32 v124, v124
	v_rcp_f32_e32 v125, v125
	v_fmac_f32_e32 v128, v134, v134
	v_add_f32_e32 v0, v128, v0
	v_lshlrev_b32_e32 v128, 16, v204
	v_and_b32_e32 v129, 0xffff0000, v204
	v_lshlrev_b32_e32 v132, 16, v205
	v_and_b32_e32 v133, 0xffff0000, v205
	v_add_f32_e32 v126, 1.0, v152
	v_lshlrev_b32_e32 v152, 16, v153
	v_and_b32_e32 v153, 0xffff0000, v153
	v_add_f32_e32 v127, 1.0, v154
	v_cvt_pk_fp8_f32 v203, v134, v135 op_sel:[0,0,1]
	v_lshlrev_b32_e32 v134, 16, v206
	v_and_b32_e32 v135, 0xffff0000, v206
	v_rcp_f32_e32 v126, v126
	v_rcp_f32_e32 v127, v127
	v_pk_fma_f32 v[122:123], v[122:123], v[152:153], v[132:133]
	v_pk_fma_f32 v[120:121], v[120:121], v[198:199], v[128:129]
	v_pk_fma_f32 v[128:129], v[124:125], v[200:201], v[134:135]
	v_mul_f32_e32 v124, v121, v121
	v_mul_f32_e32 v125, v123, v123
	v_fmac_f32_e32 v124, v120, v120
	v_fmac_f32_e32 v125, v122, v122
	v_cvt_pk_fp8_f32 v202, v196, v197 op_sel:[0,0,1]
	v_lshlrev_b32_e32 v196, 16, v207
	v_and_b32_e32 v197, 0xffff0000, v207
	v_lshlrev_b32_e32 v154, 16, v155
	v_and_b32_e32 v155, 0xffff0000, v155
	v_add_f32_e32 v124, v124, v125
	v_mul_f32_e32 v125, v129, v129
	v_pk_fma_f32 v[132:133], v[126:127], v[154:155], v[196:197]
	v_fmac_f32_e32 v125, v128, v128
	v_add_f32_e32 v124, v125, v124
	v_mul_f32_e32 v125, v133, v133
	v_fmac_f32_e32 v125, v132, v132
	v_add_f32_e32 v124, v125, v124
	v_add_f32_e32 v0, v0, v124
	v_xor_b32_e32 v124, 16, v190
	v_cmp_lt_i32_e32 vcc, v124, v192
	v_mov_b32_e32 v134, v1
	global_store_dwordx2 v[130:131], v[202:203], off
	v_cndmask_b32_e32 v124, v190, v124, vcc
	v_lshlrev_b32_e32 v124, 2, v124
	ds_bpermute_b32 v125, v124, v0
	v_cvt_pk_fp8_f32 v134, v120, v121
	v_cvt_pk_bf16_f32 v126, v120, v121
	v_xor_b32_e32 v120, 32, v190
	v_mov_b32_e32 v135, v1
	v_cmp_lt_i32_e32 vcc, v120, v192
	v_cvt_pk_fp8_f32 v135, v128, v129
	s_waitcnt lgkmcnt(0)
	v_add_f32_e32 v0, v0, v125
	v_cndmask_b32_e32 v120, v190, v120, vcc
	v_lshlrev_b32_e32 v125, 2, v120
	ds_bpermute_b32 v120, v125, v0
	v_cvt_pk_fp8_f32 v134, v122, v123 op_sel:[0,0,1]
	v_cvt_pk_fp8_f32 v135, v132, v133 op_sel:[0,0,1]
	v_cvt_pk_bf16_f32 v127, v122, v123
	v_cvt_pk_bf16_f32 v128, v128, v129
	v_cvt_pk_bf16_f32 v129, v132, v133
	global_store_dwordx4 v[184:185], v[126:129], off offset:256
	global_store_dwordx2 v[130:131], v[134:135], off offset:128
	s_and_saveexec_b64 s[2:3], s[40:41]
	s_cbranch_execz .LBB0_1286
	s_ashr_i32 s7, s6, 31
	s_lshl_b64 s[4:5], s[6:7], 19
	s_add_u32 s4, s39, s4
	s_addc_u32 s5, s42, s5
	s_waitcnt lgkmcnt(0)
	v_add_f32_e32 v0, v0, v120
	v_lshl_add_u64 v[120:121], v[178:179], 4, s[4:5]
	s_lshl_b32 s74, s53, 2
	v_lshl_add_u64 v[120:121], v[120:121], 0, s[74:75]
	global_store_dword v[120:121], v0, off
